# conv2d: rows paired and lanes exchanged (DPP) so each store is 16 B per lane (2 dwordx4 instead of 4 dwordx2 per column step)
# baseline (speedup 1.0000x reference)
.LBB0_928:
	s_cmp_lt_i32 s76, 12
	s_cselect_b64 s[16:17], -1, 0
	s_and_b64 s[4:5], s[16:17], s[46:47]
	s_andn2_b64 vcc, exec, s[4:5]
	s_cbranch_vccnz .LBB0_979
	s_and_b32 s4, s2, 7
	s_mulk_i32 s4, 0x2c0
	s_and_b32 s5, s2, -8
	s_and_b32 s3, s38, 7
	s_lshl_b32 s10, s2, 3
	s_add_i32 s11, s4, s5
	s_add_i32 s12, s4, 0x2c0
	s_cmp_eq_u32 s3, 0
	s_cselect_b64 s[6:7], -1, 0
	s_and_b64 s[4:5], s[6:7], exec
	s_cselect_b32 s3, s11, s10
	s_waitcnt vmcnt(0)
	v_add_u32_e32 v166, s3, v197
	s_cselect_b32 s27, s12, 0x1600
	s_mov_b64 s[8:9], s[0:1]
	s_movk_i32 s3, 0x1600
	v_cmp_gt_i32_e32 vcc, s27, v166
	s_and_saveexec_b64 s[18:19], vcc
	s_cbranch_execz .LBB0_978
	s_load_dwordx4 s[12:15], s[8:9], 0xb8
	s_load_dwordx2 s[20:21], s[8:9], 0xe0
	s_and_b32 s10, s38, -8
	s_lshl_b32 s11, s38, 3
	s_and_b64 s[4:5], s[6:7], exec
	s_cselect_b32 s29, s10, s11
	s_waitcnt lgkmcnt(0)
	s_add_u32 s22, s20, 0xd200e00
	v_lshlrev_b32_e32 v0, 2, v196
	s_addc_u32 s23, s21, 0
	v_and_b32_e32 v167, 0xfc, v0
	s_mov_b64 s[24:25], 0
	s_mov_b32 s39, 0x2e8ba2e9
	s_movk_i32 s48, 0x2000
	s_movk_i32 s49, 0x5000
	s_mov_b32 s50, 0x8000
	s_mov_b32 s51, 0xb000
	s_mov_b32 s52, 0xd000
	s_mov_b32 s53, 0x10000
	s_mov_b32 s54, 0x13000
	s_mov_b32 s55, 0x16000
	s_movk_i32 s56, 0x7c
	s_mov_b32 s57, 0x2c00000
	v_mov_b64_e32 v[40:41], s[22:23]
	s_movk_i32 s58, 0x80
	v_mov_b32_e32 v42, 0
	s_movk_i32 s59, 0x100
	s_mov_b32 s60, 0x160000
	s_mov_b32 s61, 0x23200000
	s_mov_b32 s26, 0x3dd2d3e7
	s_mov_b32 s28, 0xc0135761
	s_mov_b32 s62, 0x23202000
	s_mov_b32 s63, 0x23203000
	s_mov_b32 s88, s61
	s_mov_b32 s89, 0
	s_mov_b32 s90, s63
	s_mov_b32 s91, 0
	v_and_b32_e32 v190, 1, v196
	v_cmp_eq_u32_e64 s[84:85], 0, v190
	s_mov_b32 s86, -8
	s_mov_b32 s87, -1
	s_branch .LBB0_932

.LBB0_949:
	s_or_b64 exec, exec, s[10:11]
	v_add_co_u32_e32 v86, vcc, s63, v128
	v_pk_mul_f32 v[94:95], v[6:7], v[76:77]
	s_nop 0
	v_addc_co_u32_e32 v87, vcc, 0, v129, vcc
	flat_load_dwordx2 v[88:89], v[86:87] offset:2560
	v_lshl_add_u64 v[178:179], v[116:117], 0, s[90:91]
	v_lshl_add_u64 v[180:181], v[110:111], 0, s[90:91]
	v_lshl_add_u64 v[182:183], v[100:101], 0, s[90:91]
	global_load_dwordx2 v[184:185], v[178:179], off offset:2560
	global_load_dwordx2 v[186:187], v[180:181], off offset:2560
	global_load_dwordx2 v[188:189], v[182:183], off offset:2560
	v_pk_mul_f32 v[96:97], v[4:5], v[72:73]
	v_lshlrev_b32_e32 v62, 16, v148
	v_and_b32_e32 v63, 0xffff0000, v148
	v_lshlrev_b32_e32 v64, 16, v149
	v_and_b32_e32 v65, 0xffff0000, v149
	v_pk_mul_f32 v[106:107], v[18:19], v[80:81]
	v_pk_mul_f32 v[108:109], v[16:17], v[78:79]
	v_pk_fma_f32 v[94:95], v[2:3], v[144:145], v[94:95]
	v_pk_fma_f32 v[96:97], v[0:1], v[142:143], v[96:97]
	v_lshlrev_b32_e32 v66, 16, v152
	v_and_b32_e32 v67, 0xffff0000, v152
	v_lshlrev_b32_e32 v68, 16, v153
	v_and_b32_e32 v69, 0xffff0000, v153
	v_lshlrev_b32_e32 v70, 16, v150
	v_and_b32_e32 v71, 0xffff0000, v150
	v_lshlrev_b32_e32 v74, 16, v151
	v_and_b32_e32 v75, 0xffff0000, v151
	v_pk_mul_f32 v[148:149], v[30:31], v[84:85]
	v_pk_mul_f32 v[150:151], v[28:29], v[82:83]
	v_pk_fma_f32 v[106:107], v[14:15], v[136:137], v[106:107]
	v_pk_fma_f32 v[108:109], v[12:13], v[134:135], v[108:109]
	v_pk_fma_f32 v[94:95], v[10:11], v[64:65], v[94:95]
	v_pk_fma_f32 v[96:97], v[8:9], v[62:63], v[96:97]
	v_pk_fma_f32 v[142:143], v[26:27], v[126:127], v[148:149]
	v_pk_fma_f32 v[144:145], v[24:25], v[122:123], v[150:151]
	v_pk_fma_f32 v[106:107], v[22:23], v[68:69], v[106:107]
	v_pk_fma_f32 v[108:109], v[20:21], v[66:67], v[108:109]
	v_pk_add_f32 v[94:95], v[38:39], v[94:95]
	v_pk_add_f32 v[96:97], v[36:37], v[96:97]
	v_pk_fma_f32 v[142:143], v[34:35], v[74:75], v[142:143]
	v_pk_fma_f32 v[144:145], v[32:33], v[70:71], v[144:145]
	v_pk_add_f32 v[94:95], v[106:107], v[94:95]
	v_pk_add_f32 v[96:97], v[108:109], v[96:97]
	v_pk_add_f32 v[94:95], v[142:143], v[94:95]
	v_pk_add_f32 v[96:97], v[144:145], v[96:97]
	v_mov_b64_e32 v[128:129], s[28:29]
	v_pk_mul_f32 v[106:107], v[94:95], v[94:95]
	v_pk_mul_f32 v[108:109], v[96:97], v[96:97]
	v_pk_fma_f32 v[106:107], v[106:107], s[26:27], v[128:129] op_sel_hi:[1,0,0] neg_lo:[1,0,0] neg_hi:[1,0,0]
	v_pk_fma_f32 v[108:109], v[108:109], s[26:27], v[128:129] op_sel_hi:[1,0,0] neg_lo:[1,0,0] neg_hi:[1,0,0]
	v_pk_mul_f32 v[106:107], v[94:95], v[106:107]
	v_pk_mul_f32 v[108:109], v[96:97], v[108:109]
	v_exp_f32_e32 v106, v106
	v_exp_f32_e32 v108, v108
	v_exp_f32_e32 v109, v109
	v_exp_f32_e32 v107, v107
	v_add_co_u32_e32 v116, vcc, s63, v116
	v_pk_add_f32 v[108:109], v[108:109], 1.0 op_sel_hi:[1,0]
	v_pk_add_f32 v[106:107], v[106:107], 1.0 op_sel_hi:[1,0]
	v_rcp_f32_e32 v108, v108
	v_rcp_f32_e32 v109, v109
	v_rcp_f32_e32 v106, v106
	v_rcp_f32_e32 v107, v107
	v_addc_co_u32_e32 v117, vcc, 0, v117, vcc
	v_pk_mul_f32 v[96:97], v[96:97], v[108:109]
	v_pk_mul_f32 v[94:95], v[94:95], v[106:107]
	v_pk_mul_f32 v[108:109], v[18:19], v[84:85]
	v_pk_mul_f32 v[142:143], v[16:17], v[82:83]
	v_pk_mul_f32 v[144:145], v[30:31], v[92:93]
	v_pk_fma_f32 v[108:109], v[14:15], v[126:127], v[108:109]
	v_add_co_u32_e32 v110, vcc, s63, v110
	v_pk_fma_f32 v[108:109], v[22:23], v[74:75], v[108:109]
	s_nop 0
	v_addc_co_u32_e32 v111, vcc, 0, v111, vcc
	v_add_co_u32_e32 v100, vcc, s63, v100
	s_waitcnt vmcnt(0) lgkmcnt(0)
	v_mov_b64_e32 v[148:149], v[158:159]
	v_addc_co_u32_e32 v101, vcc, 0, v101, vcc
	v_mov_b64_e32 v[152:153], v[154:155]
	v_mov_b64_e32 v[150:151], v[156:157]
	v_lshlrev_b32_e32 v43, 16, v88
	v_and_b32_e32 v88, 0xffff0000, v88
	v_lshlrev_b32_e32 v106, 16, v89
	v_and_b32_e32 v89, 0xffff0000, v89
	v_mul_f32_e32 v88, v97, v88
	v_mul_f32_e32 v89, v95, v89
	v_mul_f32_e32 v43, v96, v43
	v_mul_f32_e32 v94, v94, v106
	v_cvt_pk_bf16_f32 v88, v43, v88
	v_cvt_pk_bf16_f32 v89, v94, v89
	v_mov_b64_e32 v[190:191], v[88:89]
	v_mov_b64_e32 v[192:193], v[86:87]
	v_mov_b64_e32 v[94:95], v[184:185]
	v_pk_mul_f32 v[96:97], v[6:7], v[80:81]
	v_pk_mul_f32 v[106:107], v[4:5], v[78:79]
	v_pk_fma_f32 v[96:97], v[2:3], v[136:137], v[96:97]
	v_pk_fma_f32 v[106:107], v[0:1], v[134:135], v[106:107]
	v_lshlrev_b32_e32 v86, 16, v146
	v_and_b32_e32 v87, 0xffff0000, v146
	v_lshlrev_b32_e32 v88, 16, v147
	v_and_b32_e32 v89, 0xffff0000, v147
	v_pk_mul_f32 v[146:147], v[28:29], v[90:91]
	v_pk_fma_f32 v[134:135], v[12:13], v[122:123], v[142:143]
	v_pk_fma_f32 v[96:97], v[10:11], v[68:69], v[96:97]
	v_pk_fma_f32 v[106:107], v[8:9], v[66:67], v[106:107]
	v_pk_fma_f32 v[136:137], v[26:27], v[120:121], v[144:145]
	v_pk_fma_f32 v[142:143], v[24:25], v[118:119], v[146:147]
	v_pk_fma_f32 v[134:135], v[20:21], v[70:71], v[134:135]
	v_pk_add_f32 v[96:97], v[38:39], v[96:97]
	v_pk_add_f32 v[106:107], v[36:37], v[106:107]
	v_pk_fma_f32 v[136:137], v[34:35], v[88:89], v[136:137]
	v_pk_fma_f32 v[142:143], v[32:33], v[86:87], v[142:143]
	v_pk_add_f32 v[96:97], v[108:109], v[96:97]
	v_pk_add_f32 v[106:107], v[134:135], v[106:107]
	v_pk_add_f32 v[96:97], v[136:137], v[96:97]
	v_pk_add_f32 v[106:107], v[142:143], v[106:107]
	v_pk_mul_f32 v[108:109], v[96:97], v[96:97]
	v_pk_mul_f32 v[134:135], v[106:107], v[106:107]
	v_pk_fma_f32 v[108:109], v[108:109], s[26:27], v[128:129] op_sel_hi:[1,0,0] neg_lo:[1,0,0] neg_hi:[1,0,0]
	v_pk_fma_f32 v[134:135], v[134:135], s[26:27], v[128:129] op_sel_hi:[1,0,0] neg_lo:[1,0,0] neg_hi:[1,0,0]
	v_pk_mul_f32 v[108:109], v[96:97], v[108:109]
	v_pk_mul_f32 v[134:135], v[106:107], v[134:135]
	v_exp_f32_e32 v108, v108
	v_exp_f32_e32 v134, v134
	v_exp_f32_e32 v135, v135
	v_exp_f32_e32 v109, v109
	v_pk_mul_f32 v[136:137], v[30:31], v[102:103]
	v_pk_mul_f32 v[142:143], v[28:29], v[98:99]
	v_pk_add_f32 v[134:135], v[134:135], 1.0 op_sel_hi:[1,0]
	v_pk_add_f32 v[108:109], v[108:109], 1.0 op_sel_hi:[1,0]
	v_rcp_f32_e32 v134, v134
	v_rcp_f32_e32 v135, v135
	v_rcp_f32_e32 v108, v108
	v_rcp_f32_e32 v109, v109
	v_mov_b64_e32 v[146:147], v[160:161]
	v_pk_mul_f32 v[106:107], v[106:107], v[134:135]
	v_pk_mul_f32 v[134:135], v[16:17], v[90:91]
	v_pk_mul_f32 v[96:97], v[96:97], v[108:109]
	s_nop 0
	v_lshlrev_b32_e32 v43, 16, v94
	v_and_b32_e32 v94, 0xffff0000, v94
	v_lshlrev_b32_e32 v108, 16, v95
	v_and_b32_e32 v95, 0xffff0000, v95
	v_mul_f32_e32 v94, v107, v94
	v_mul_f32_e32 v95, v97, v95
	v_mul_f32_e32 v43, v106, v43
	v_mul_f32_e32 v96, v96, v108
	v_cvt_pk_bf16_f32 v94, v43, v94
	v_cvt_pk_bf16_f32 v95, v96, v95
	s_nop 1
	v_mov_b32_dpp v204, v190 quad_perm:[1,0,3,2] row_mask:0xf bank_mask:0xf
	v_mov_b32_dpp v205, v191 quad_perm:[1,0,3,2] row_mask:0xf bank_mask:0xf
	v_mov_b32_dpp v206, v94 quad_perm:[1,0,3,2] row_mask:0xf bank_mask:0xf
	v_mov_b32_dpp v207, v95 quad_perm:[1,0,3,2] row_mask:0xf bank_mask:0xf
	v_lshl_add_u64 v[210:211], v[116:117], 0, s[86:87]
	v_cndmask_b32_e64 v200, v206, v190, s[84:85]
	v_cndmask_b32_e64 v201, v207, v191, s[84:85]
	v_cndmask_b32_e64 v202, v94, v204, s[84:85]
	v_cndmask_b32_e64 v203, v95, v205, s[84:85]
	v_cndmask_b32_e64 v208, v210, v192, s[84:85]
	v_cndmask_b32_e64 v209, v211, v193, s[84:85]
	flat_store_dwordx4 v[208:209], v[200:203] offset:2560
	v_mov_b64_e32 v[106:107], v[186:187]
	v_pk_mul_f32 v[108:109], v[6:7], v[84:85]
	v_pk_mul_f32 v[116:117], v[4:5], v[82:83]
	v_lshlrev_b32_e32 v94, 16, v124
	v_and_b32_e32 v95, 0xffff0000, v124
	v_lshlrev_b32_e32 v96, 16, v125
	v_and_b32_e32 v97, 0xffff0000, v125
	v_pk_mul_f32 v[124:125], v[18:19], v[92:93]
	v_pk_fma_f32 v[108:109], v[2:3], v[126:127], v[108:109]
	v_pk_fma_f32 v[116:117], v[0:1], v[122:123], v[116:117]
	v_pk_fma_f32 v[122:123], v[14:15], v[120:121], v[124:125]
	v_pk_fma_f32 v[124:125], v[12:13], v[118:119], v[134:135]
	v_pk_fma_f32 v[108:109], v[10:11], v[74:75], v[108:109]
	v_pk_fma_f32 v[116:117], v[8:9], v[70:71], v[116:117]
	v_pk_fma_f32 v[126:127], v[26:27], v[132:133], v[136:137]
	v_pk_fma_f32 v[134:135], v[24:25], v[130:131], v[142:143]
	v_pk_fma_f32 v[122:123], v[22:23], v[88:89], v[122:123]
	v_pk_fma_f32 v[124:125], v[20:21], v[86:87], v[124:125]
	v_pk_add_f32 v[108:109], v[38:39], v[108:109]
	v_pk_add_f32 v[116:117], v[36:37], v[116:117]
	v_pk_fma_f32 v[126:127], v[34:35], v[96:97], v[126:127]
	v_pk_fma_f32 v[134:135], v[32:33], v[94:95], v[134:135]
	v_pk_add_f32 v[108:109], v[122:123], v[108:109]
	v_pk_add_f32 v[116:117], v[124:125], v[116:117]
	v_pk_add_f32 v[108:109], v[126:127], v[108:109]
	v_pk_add_f32 v[116:117], v[134:135], v[116:117]
	v_pk_mul_f32 v[122:123], v[108:109], v[108:109]
	v_pk_mul_f32 v[124:125], v[116:117], v[116:117]
	v_pk_fma_f32 v[122:123], v[122:123], s[26:27], v[128:129] op_sel_hi:[1,0,0] neg_lo:[1,0,0] neg_hi:[1,0,0]
	v_pk_fma_f32 v[124:125], v[124:125], s[26:27], v[128:129] op_sel_hi:[1,0,0] neg_lo:[1,0,0] neg_hi:[1,0,0]
	v_pk_mul_f32 v[122:123], v[108:109], v[122:123]
	v_pk_mul_f32 v[124:125], v[116:117], v[124:125]
	v_exp_f32_e32 v122, v122
	v_exp_f32_e32 v124, v124
	v_exp_f32_e32 v125, v125
	v_exp_f32_e32 v123, v123
	v_pk_mul_f32 v[126:127], v[30:31], v[114:115]
	v_pk_mul_f32 v[134:135], v[28:29], v[112:113]
	v_pk_add_f32 v[124:125], v[124:125], 1.0 op_sel_hi:[1,0]
	v_pk_add_f32 v[122:123], v[122:123], 1.0 op_sel_hi:[1,0]
	v_rcp_f32_e32 v124, v124
	v_rcp_f32_e32 v125, v125
	v_rcp_f32_e32 v122, v122
	v_rcp_f32_e32 v123, v123
	v_pk_mul_f32 v[116:117], v[116:117], v[124:125]
	v_pk_mul_f32 v[124:125], v[16:17], v[98:99]
	v_pk_mul_f32 v[108:109], v[108:109], v[122:123]
	s_nop 0
	v_lshlrev_b32_e32 v43, 16, v106
	v_and_b32_e32 v106, 0xffff0000, v106
	v_lshlrev_b32_e32 v122, 16, v107
	v_and_b32_e32 v107, 0xffff0000, v107
	v_mul_f32_e32 v106, v117, v106
	v_mul_f32_e32 v107, v109, v107
	v_mul_f32_e32 v43, v116, v43
	v_mul_f32_e32 v108, v108, v122
	v_cvt_pk_bf16_f32 v106, v43, v106
	v_cvt_pk_bf16_f32 v107, v108, v107
	v_mov_b64_e32 v[194:195], v[106:107]
	v_mov_b64_e32 v[198:199], v[110:111]
	v_mov_b64_e32 v[110:111], v[188:189]
	v_lshlrev_b32_e32 v106, 16, v104
	v_and_b32_e32 v107, 0xffff0000, v104
	v_lshlrev_b32_e32 v108, 16, v105
	v_and_b32_e32 v109, 0xffff0000, v105
	v_pk_mul_f32 v[104:105], v[6:7], v[92:93]
	v_pk_mul_f32 v[116:117], v[4:5], v[90:91]
	v_pk_mul_f32 v[122:123], v[18:19], v[102:103]
	v_pk_fma_f32 v[104:105], v[2:3], v[120:121], v[104:105]
	v_pk_fma_f32 v[116:117], v[0:1], v[118:119], v[116:117]
	v_pk_fma_f32 v[118:119], v[14:15], v[132:133], v[122:123]
	v_pk_fma_f32 v[104:105], v[10:11], v[88:89], v[104:105]
	v_pk_fma_f32 v[120:121], v[12:13], v[130:131], v[124:125]
	v_pk_fma_f32 v[122:123], v[26:27], v[140:141], v[126:127]
	v_pk_fma_f32 v[116:117], v[8:9], v[86:87], v[116:117]
	v_pk_fma_f32 v[118:119], v[22:23], v[96:97], v[118:119]
	v_pk_add_f32 v[104:105], v[38:39], v[104:105]
	v_pk_fma_f32 v[124:125], v[24:25], v[138:139], v[134:135]
	v_pk_fma_f32 v[120:121], v[20:21], v[94:95], v[120:121]
	v_pk_fma_f32 v[122:123], v[34:35], v[108:109], v[122:123]
	v_pk_add_f32 v[116:117], v[36:37], v[116:117]
	v_pk_add_f32 v[104:105], v[118:119], v[104:105]
	v_pk_fma_f32 v[124:125], v[32:33], v[106:107], v[124:125]
	v_pk_add_f32 v[116:117], v[120:121], v[116:117]
	v_pk_add_f32 v[104:105], v[122:123], v[104:105]
	v_pk_add_f32 v[116:117], v[124:125], v[116:117]
	v_pk_mul_f32 v[118:119], v[104:105], v[104:105]
	v_pk_mul_f32 v[120:121], v[116:117], v[116:117]
	v_pk_fma_f32 v[118:119], v[118:119], s[26:27], v[128:129] op_sel_hi:[1,0,0] neg_lo:[1,0,0] neg_hi:[1,0,0]
	v_pk_fma_f32 v[120:121], v[120:121], s[26:27], v[128:129] op_sel_hi:[1,0,0] neg_lo:[1,0,0] neg_hi:[1,0,0]
	v_pk_mul_f32 v[118:119], v[104:105], v[118:119]
	v_pk_mul_f32 v[120:121], v[116:117], v[120:121]
	v_exp_f32_e32 v118, v118
	v_exp_f32_e32 v119, v119
	v_exp_f32_e32 v120, v120
	v_exp_f32_e32 v121, v121
	v_mov_b64_e32 v[124:125], v[162:163]
	v_pk_add_f32 v[118:119], v[118:119], 1.0 op_sel_hi:[1,0]
	v_pk_add_f32 v[120:121], v[120:121], 1.0 op_sel_hi:[1,0]
	v_rcp_f32_e32 v118, v118
	v_rcp_f32_e32 v119, v119
	v_rcp_f32_e32 v120, v120
	v_rcp_f32_e32 v121, v121
	v_pk_mul_f32 v[104:105], v[104:105], v[118:119]
	v_pk_mul_f32 v[116:117], v[116:117], v[120:121]
	s_nop 0
	v_lshlrev_b32_e32 v118, 16, v111
	v_and_b32_e32 v111, 0xffff0000, v111
	v_lshlrev_b32_e32 v43, 16, v110
	v_and_b32_e32 v110, 0xffff0000, v110
	v_mul_f32_e32 v105, v105, v111
	v_mul_f32_e32 v43, v116, v43
	v_mul_f32_e32 v110, v117, v110
	v_mul_f32_e32 v116, v104, v118
	v_cvt_pk_bf16_f32 v104, v43, v110
	v_cvt_pk_bf16_f32 v105, v116, v105
	s_nop 1
	v_mov_b32_dpp v204, v194 quad_perm:[1,0,3,2] row_mask:0xf bank_mask:0xf
	v_mov_b32_dpp v205, v195 quad_perm:[1,0,3,2] row_mask:0xf bank_mask:0xf
	v_mov_b32_dpp v206, v104 quad_perm:[1,0,3,2] row_mask:0xf bank_mask:0xf
	v_mov_b32_dpp v207, v105 quad_perm:[1,0,3,2] row_mask:0xf bank_mask:0xf
	v_lshl_add_u64 v[210:211], v[100:101], 0, s[86:87]
	v_cndmask_b32_e64 v200, v206, v194, s[84:85]
	v_cndmask_b32_e64 v201, v207, v195, s[84:85]
	v_cndmask_b32_e64 v202, v104, v204, s[84:85]
	v_cndmask_b32_e64 v203, v105, v205, s[84:85]
	v_cndmask_b32_e64 v208, v210, v198, s[84:85]
	v_cndmask_b32_e64 v209, v211, v199, s[84:85]
	flat_store_dwordx4 v[208:209], v[200:203] offset:2560
	v_mov_b64_e32 v[104:105], v[164:165]

.LBB0_959:
	s_or_b64 exec, exec, s[10:11]
	v_add_co_u32_e32 v130, vcc, s61, v128
	v_lshlrev_b32_e32 v142, 16, v118
	s_nop 0
	v_addc_co_u32_e32 v131, vcc, 0, v129, vcc
	flat_load_dwordx2 v[138:139], v[130:131] offset:3584
	v_lshl_add_u64 v[178:179], v[116:117], 0, s[88:89]
	v_lshl_add_u64 v[180:181], v[110:111], 0, s[88:89]
	v_lshl_add_u64 v[182:183], v[100:101], 0, s[88:89]
	global_load_dwordx2 v[184:185], v[178:179], off offset:3584
	global_load_dwordx2 v[186:187], v[180:181], off offset:3584
	global_load_dwordx2 v[188:189], v[182:183], off offset:3584
	v_and_b32_e32 v143, 0xffff0000, v118
	v_lshlrev_b32_e32 v144, 16, v119
	v_and_b32_e32 v145, 0xffff0000, v119
	v_pk_mul_f32 v[118:119], v[6:7], v[64:65]
	v_pk_mul_f32 v[156:157], v[4:5], v[62:63]
	v_pk_mul_f32 v[158:159], v[18:19], v[68:69]
	v_pk_fma_f32 v[118:119], v[2:3], v[76:77], v[118:119]
	v_lshlrev_b32_e32 v136, 16, v123
	v_and_b32_e32 v137, 0xffff0000, v123
	v_pk_mul_f32 v[160:161], v[16:17], v[66:67]
	v_pk_mul_f32 v[162:163], v[30:31], v[74:75]
	v_pk_fma_f32 v[156:157], v[0:1], v[72:73], v[156:157]
	v_pk_fma_f32 v[158:159], v[14:15], v[80:81], v[158:159]
	v_pk_fma_f32 v[118:119], v[10:11], v[144:145], v[118:119]
	v_lshlrev_b32_e32 v134, 16, v122
	v_and_b32_e32 v135, 0xffff0000, v122
	v_lshlrev_b32_e32 v122, 16, v126
	v_and_b32_e32 v123, 0xffff0000, v126
	v_lshlrev_b32_e32 v126, 16, v127
	v_and_b32_e32 v127, 0xffff0000, v127
	v_pk_mul_f32 v[164:165], v[28:29], v[70:71]
	v_pk_fma_f32 v[160:161], v[12:13], v[78:79], v[160:161]
	v_pk_fma_f32 v[162:163], v[26:27], v[84:85], v[162:163]
	v_pk_fma_f32 v[156:157], v[8:9], v[142:143], v[156:157]
	v_pk_fma_f32 v[158:159], v[22:23], v[136:137], v[158:159]
	v_pk_add_f32 v[118:119], v[38:39], v[118:119]
	v_pk_fma_f32 v[164:165], v[24:25], v[82:83], v[164:165]
	v_pk_fma_f32 v[160:161], v[20:21], v[134:135], v[160:161]
	v_pk_fma_f32 v[162:163], v[34:35], v[126:127], v[162:163]
	v_pk_add_f32 v[156:157], v[36:37], v[156:157]
	v_pk_add_f32 v[118:119], v[118:119], v[158:159]
	v_pk_fma_f32 v[164:165], v[32:33], v[122:123], v[164:165]
	v_pk_add_f32 v[156:157], v[156:157], v[160:161]
	v_pk_add_f32 v[118:119], v[118:119], v[162:163]
	v_mov_b64_e32 v[154:155], s[28:29]
	v_pk_add_f32 v[156:157], v[156:157], v[164:165]
	v_pk_mul_f32 v[158:159], v[118:119], v[118:119]
	v_pk_mul_f32 v[160:161], v[156:157], v[156:157]
	v_pk_fma_f32 v[158:159], v[158:159], s[26:27], v[154:155] op_sel_hi:[1,0,0] neg_lo:[1,0,0] neg_hi:[1,0,0]
	v_pk_fma_f32 v[160:161], v[160:161], s[26:27], v[154:155] op_sel_hi:[1,0,0] neg_lo:[1,0,0] neg_hi:[1,0,0]
	v_pk_mul_f32 v[158:159], v[118:119], v[158:159]
	v_pk_mul_f32 v[160:161], v[156:157], v[160:161]
	v_exp_f32_e32 v158, v158
	v_exp_f32_e32 v159, v159
	v_exp_f32_e32 v160, v160
	v_exp_f32_e32 v161, v161
	v_add_co_u32_e32 v162, vcc, s61, v116
	v_pk_add_f32 v[158:159], v[158:159], 1.0 op_sel_hi:[1,0]
	v_pk_add_f32 v[160:161], v[160:161], 1.0 op_sel_hi:[1,0]
	v_rcp_f32_e32 v158, v158
	v_rcp_f32_e32 v159, v159
	v_rcp_f32_e32 v160, v160
	v_rcp_f32_e32 v161, v161
	v_addc_co_u32_e32 v163, vcc, 0, v117, vcc
	v_pk_mul_f32 v[118:119], v[118:119], v[158:159]
	v_pk_mul_f32 v[156:157], v[156:157], v[160:161]
	v_pk_mul_f32 v[160:161], v[16:17], v[70:71]
	v_pk_mul_f32 v[164:165], v[30:31], v[88:89]
	v_pk_mul_f32 v[170:171], v[28:29], v[86:87]
	v_pk_fma_f32 v[160:161], v[12:13], v[82:83], v[160:161]
	v_pk_fma_f32 v[170:171], v[24:25], v[90:91], v[170:171]
	v_pk_fma_f32 v[164:165], v[26:27], v[92:93], v[164:165]
	v_pk_fma_f32 v[160:161], v[20:21], v[122:123], v[160:161]
	v_pk_mul_f32 v[172:173], v[28:29], v[94:95]
	v_pk_mul_f32 v[174:175], v[28:29], v[106:107]
	v_pk_fma_f32 v[172:173], v[24:25], v[98:99], v[172:173]
	v_pk_fma_f32 v[174:175], v[24:25], v[112:113], v[174:175]
	s_waitcnt vmcnt(0) lgkmcnt(0)
	v_lshlrev_b32_e32 v158, 16, v139
	v_and_b32_e32 v139, 0xffff0000, v139
	v_lshlrev_b32_e32 v43, 16, v138
	v_and_b32_e32 v138, 0xffff0000, v138
	v_mul_f32_e32 v119, v119, v139
	v_mul_f32_e32 v43, v156, v43
	v_mul_f32_e32 v138, v157, v138
	v_mul_f32_e32 v156, v118, v158
	v_cvt_pk_bf16_f32 v118, v43, v138
	v_cvt_pk_bf16_f32 v119, v156, v119
	v_mov_b64_e32 v[190:191], v[118:119]
	v_mov_b64_e32 v[192:193], v[130:131]
	v_mov_b64_e32 v[130:131], v[184:185]
	v_pk_mul_f32 v[138:139], v[6:7], v[68:69]
	v_pk_mul_f32 v[156:157], v[4:5], v[66:67]
	v_pk_mul_f32 v[158:159], v[18:19], v[74:75]
	v_pk_fma_f32 v[156:157], v[0:1], v[78:79], v[156:157]
	v_pk_fma_f32 v[138:139], v[2:3], v[80:81], v[138:139]
	v_pk_fma_f32 v[158:159], v[14:15], v[84:85], v[158:159]
	v_pk_fma_f32 v[138:139], v[10:11], v[136:137], v[138:139]
	v_pk_fma_f32 v[156:157], v[8:9], v[134:135], v[156:157]
	v_lshlrev_b32_e32 v118, 16, v120
	v_and_b32_e32 v119, 0xffff0000, v120
	v_lshlrev_b32_e32 v120, 16, v121
	v_and_b32_e32 v121, 0xffff0000, v121
	v_pk_fma_f32 v[158:159], v[22:23], v[126:127], v[158:159]
	v_pk_add_f32 v[156:157], v[36:37], v[156:157]
	v_pk_add_f32 v[138:139], v[38:39], v[138:139]
	v_pk_fma_f32 v[164:165], v[34:35], v[120:121], v[164:165]
	v_pk_fma_f32 v[170:171], v[32:33], v[118:119], v[170:171]
	v_pk_add_f32 v[138:139], v[138:139], v[158:159]
	v_pk_add_f32 v[156:157], v[156:157], v[160:161]
	v_pk_add_f32 v[138:139], v[138:139], v[164:165]
	v_pk_add_f32 v[156:157], v[156:157], v[170:171]
	v_pk_mul_f32 v[158:159], v[138:139], v[138:139]
	v_pk_mul_f32 v[160:161], v[156:157], v[156:157]
	v_pk_fma_f32 v[158:159], v[158:159], s[26:27], v[154:155] op_sel_hi:[1,0,0] neg_lo:[1,0,0] neg_hi:[1,0,0]
	v_pk_fma_f32 v[160:161], v[160:161], s[26:27], v[154:155] op_sel_hi:[1,0,0] neg_lo:[1,0,0] neg_hi:[1,0,0]
	v_pk_mul_f32 v[158:159], v[138:139], v[158:159]
	v_pk_mul_f32 v[160:161], v[156:157], v[160:161]
	v_exp_f32_e32 v158, v158
	v_exp_f32_e32 v160, v160
	v_exp_f32_e32 v161, v161
	v_exp_f32_e32 v159, v159
	v_add_co_u32_e32 v164, vcc, s61, v110
	v_pk_add_f32 v[160:161], v[160:161], 1.0 op_sel_hi:[1,0]
	v_pk_add_f32 v[158:159], v[158:159], 1.0 op_sel_hi:[1,0]
	v_rcp_f32_e32 v160, v160
	v_rcp_f32_e32 v161, v161
	v_rcp_f32_e32 v158, v158
	v_rcp_f32_e32 v159, v159
	v_addc_co_u32_e32 v165, vcc, 0, v111, vcc
	v_pk_mul_f32 v[156:157], v[156:157], v[160:161]
	v_pk_mul_f32 v[138:139], v[138:139], v[158:159]
	v_pk_mul_f32 v[160:161], v[18:19], v[88:89]
	v_pk_mul_f32 v[170:171], v[30:31], v[96:97]
	v_pk_fma_f32 v[160:161], v[14:15], v[92:93], v[160:161]
	v_pk_fma_f32 v[170:171], v[26:27], v[102:103], v[170:171]
	v_pk_fma_f32 v[160:161], v[22:23], v[120:121], v[160:161]
	s_nop 0
	v_lshlrev_b32_e32 v43, 16, v130
	v_and_b32_e32 v130, 0xffff0000, v130
	v_lshlrev_b32_e32 v158, 16, v131
	v_and_b32_e32 v131, 0xffff0000, v131
	v_mul_f32_e32 v130, v157, v130
	v_mul_f32_e32 v131, v139, v131
	v_mul_f32_e32 v43, v156, v43
	v_mul_f32_e32 v138, v138, v158
	v_cvt_pk_bf16_f32 v130, v43, v130
	v_cvt_pk_bf16_f32 v131, v138, v131
	s_nop 1
	v_mov_b32_dpp v204, v190 quad_perm:[1,0,3,2] row_mask:0xf bank_mask:0xf
	v_mov_b32_dpp v205, v191 quad_perm:[1,0,3,2] row_mask:0xf bank_mask:0xf
	v_mov_b32_dpp v206, v130 quad_perm:[1,0,3,2] row_mask:0xf bank_mask:0xf
	v_mov_b32_dpp v207, v131 quad_perm:[1,0,3,2] row_mask:0xf bank_mask:0xf
	v_lshl_add_u64 v[210:211], v[162:163], 0, s[86:87]
	v_cndmask_b32_e64 v200, v206, v190, s[84:85]
	v_cndmask_b32_e64 v201, v207, v191, s[84:85]
	v_cndmask_b32_e64 v202, v130, v204, s[84:85]
	v_cndmask_b32_e64 v203, v131, v205, s[84:85]
	v_cndmask_b32_e64 v208, v210, v192, s[84:85]
	v_cndmask_b32_e64 v209, v211, v193, s[84:85]
	flat_store_dwordx4 v[208:209], v[200:203] offset:3584
	v_mov_b64_e32 v[138:139], v[186:187]
	v_pk_mul_f32 v[156:157], v[6:7], v[74:75]
	v_pk_mul_f32 v[158:159], v[4:5], v[70:71]
	v_pk_mul_f32 v[162:163], v[16:17], v[86:87]
	v_pk_fma_f32 v[158:159], v[0:1], v[82:83], v[158:159]
	v_pk_fma_f32 v[156:157], v[2:3], v[84:85], v[156:157]
	v_pk_fma_f32 v[162:163], v[12:13], v[90:91], v[162:163]
	v_pk_fma_f32 v[156:157], v[10:11], v[126:127], v[156:157]
	v_pk_fma_f32 v[158:159], v[8:9], v[122:123], v[158:159]
	v_lshlrev_b32_e32 v130, 16, v132
	v_and_b32_e32 v131, 0xffff0000, v132
	v_lshlrev_b32_e32 v132, 16, v133
	v_and_b32_e32 v133, 0xffff0000, v133
	v_pk_fma_f32 v[162:163], v[20:21], v[118:119], v[162:163]
	v_pk_add_f32 v[158:159], v[36:37], v[158:159]
	v_pk_add_f32 v[156:157], v[38:39], v[156:157]
	v_pk_fma_f32 v[170:171], v[34:35], v[132:133], v[170:171]
	v_pk_fma_f32 v[172:173], v[32:33], v[130:131], v[172:173]
	v_pk_add_f32 v[156:157], v[156:157], v[160:161]
	v_pk_add_f32 v[158:159], v[158:159], v[162:163]
	v_pk_add_f32 v[156:157], v[156:157], v[170:171]
	v_pk_add_f32 v[158:159], v[158:159], v[172:173]
	v_pk_mul_f32 v[160:161], v[156:157], v[156:157]
	v_pk_mul_f32 v[162:163], v[158:159], v[158:159]
	v_pk_fma_f32 v[160:161], v[160:161], s[26:27], v[154:155] op_sel_hi:[1,0,0] neg_lo:[1,0,0] neg_hi:[1,0,0]
	v_pk_fma_f32 v[162:163], v[162:163], s[26:27], v[154:155] op_sel_hi:[1,0,0] neg_lo:[1,0,0] neg_hi:[1,0,0]
	v_pk_mul_f32 v[160:161], v[156:157], v[160:161]
	v_pk_mul_f32 v[162:163], v[158:159], v[162:163]
	v_exp_f32_e32 v160, v160
	v_exp_f32_e32 v162, v162
	v_exp_f32_e32 v163, v163
	v_exp_f32_e32 v161, v161
	v_add_co_u32_e32 v170, vcc, s61, v100
	v_pk_add_f32 v[162:163], v[162:163], 1.0 op_sel_hi:[1,0]
	v_pk_add_f32 v[160:161], v[160:161], 1.0 op_sel_hi:[1,0]
	v_rcp_f32_e32 v162, v162
	v_rcp_f32_e32 v163, v163
	v_rcp_f32_e32 v160, v160
	v_rcp_f32_e32 v161, v161
	v_addc_co_u32_e32 v171, vcc, 0, v101, vcc
	v_pk_mul_f32 v[158:159], v[158:159], v[162:163]
	v_pk_mul_f32 v[156:157], v[156:157], v[160:161]
	v_pk_mul_f32 v[162:163], v[18:19], v[96:97]
	v_pk_mul_f32 v[172:173], v[30:31], v[108:109]
	v_pk_fma_f32 v[162:163], v[14:15], v[102:103], v[162:163]
	v_pk_fma_f32 v[172:173], v[26:27], v[114:115], v[172:173]
	v_pk_fma_f32 v[162:163], v[22:23], v[132:133], v[162:163]
	s_nop 0
	v_lshlrev_b32_e32 v43, 16, v138
	v_and_b32_e32 v138, 0xffff0000, v138
	v_lshlrev_b32_e32 v160, 16, v139
	v_and_b32_e32 v139, 0xffff0000, v139
	v_mul_f32_e32 v138, v159, v138
	v_mul_f32_e32 v139, v157, v139
	v_mul_f32_e32 v43, v158, v43
	v_mul_f32_e32 v156, v156, v160
	v_cvt_pk_bf16_f32 v138, v43, v138
	v_cvt_pk_bf16_f32 v139, v156, v139
	v_mov_b64_e32 v[194:195], v[138:139]
	v_mov_b64_e32 v[198:199], v[164:165]
	v_mov_b64_e32 v[156:157], v[188:189]
	v_pk_mul_f32 v[158:159], v[6:7], v[88:89]
	v_pk_mul_f32 v[160:161], v[4:5], v[86:87]
	v_pk_mul_f32 v[164:165], v[16:17], v[94:95]
	v_pk_fma_f32 v[160:161], v[0:1], v[90:91], v[160:161]
	v_pk_fma_f32 v[158:159], v[2:3], v[92:93], v[158:159]
	v_pk_fma_f32 v[164:165], v[12:13], v[98:99], v[164:165]
	v_pk_fma_f32 v[158:159], v[10:11], v[120:121], v[158:159]
	v_pk_fma_f32 v[160:161], v[8:9], v[118:119], v[160:161]
	v_lshlrev_b32_e32 v138, 16, v140
	v_and_b32_e32 v139, 0xffff0000, v140
	v_lshlrev_b32_e32 v140, 16, v141
	v_and_b32_e32 v141, 0xffff0000, v141
	v_pk_fma_f32 v[164:165], v[20:21], v[130:131], v[164:165]
	v_pk_add_f32 v[160:161], v[36:37], v[160:161]
	v_pk_add_f32 v[158:159], v[38:39], v[158:159]
	v_pk_fma_f32 v[172:173], v[34:35], v[140:141], v[172:173]
	v_pk_fma_f32 v[174:175], v[32:33], v[138:139], v[174:175]
	v_pk_add_f32 v[158:159], v[158:159], v[162:163]
	v_pk_add_f32 v[160:161], v[160:161], v[164:165]
	v_pk_add_f32 v[158:159], v[158:159], v[172:173]
	v_pk_add_f32 v[160:161], v[160:161], v[174:175]
	v_pk_mul_f32 v[162:163], v[158:159], v[158:159]
	v_pk_mul_f32 v[164:165], v[160:161], v[160:161]
	v_add_u32_e32 v43, 1, v168
	v_pk_fma_f32 v[164:165], v[164:165], s[26:27], v[154:155] op_sel_hi:[1,0,0] neg_lo:[1,0,0] neg_hi:[1,0,0]
	v_pk_fma_f32 v[154:155], v[162:163], s[26:27], v[154:155] op_sel_hi:[1,0,0] neg_lo:[1,0,0] neg_hi:[1,0,0]
	v_pk_mul_f32 v[162:163], v[160:161], v[164:165]
	v_pk_mul_f32 v[154:155], v[158:159], v[154:155]
	v_exp_f32_e32 v162, v162
	v_exp_f32_e32 v154, v154
	v_exp_f32_e32 v155, v155
	v_exp_f32_e32 v163, v163
	v_cmp_lt_u32_e32 vcc, v43, v53
	v_pk_add_f32 v[154:155], v[154:155], 1.0 op_sel_hi:[1,0]
	v_pk_add_f32 v[162:163], v[162:163], 1.0 op_sel_hi:[1,0]
	v_rcp_f32_e32 v154, v154
	v_rcp_f32_e32 v155, v155
	v_rcp_f32_e32 v162, v162
	v_rcp_f32_e32 v163, v163
	v_pk_mul_f32 v[154:155], v[158:159], v[154:155]
	v_pk_mul_f32 v[160:161], v[160:161], v[162:163]
	s_nop 0
	v_lshlrev_b32_e32 v159, 16, v157
	v_and_b32_e32 v157, 0xffff0000, v157
	v_lshlrev_b32_e32 v158, 16, v156
	v_and_b32_e32 v156, 0xffff0000, v156
	v_mul_f32_e32 v155, v155, v157
	v_mul_f32_e32 v158, v160, v158
	v_mul_f32_e32 v156, v161, v156
	v_mul_f32_e32 v159, v154, v159
	v_cvt_pk_bf16_f32 v154, v158, v156
	v_cvt_pk_bf16_f32 v155, v159, v155
	s_nop 1
	v_mov_b32_dpp v204, v194 quad_perm:[1,0,3,2] row_mask:0xf bank_mask:0xf
	v_mov_b32_dpp v205, v195 quad_perm:[1,0,3,2] row_mask:0xf bank_mask:0xf
	v_mov_b32_dpp v206, v154 quad_perm:[1,0,3,2] row_mask:0xf bank_mask:0xf
	v_mov_b32_dpp v207, v155 quad_perm:[1,0,3,2] row_mask:0xf bank_mask:0xf
	v_lshl_add_u64 v[210:211], v[170:171], 0, s[86:87]
	v_cndmask_b32_e64 v200, v206, v194, s[84:85]
	v_cndmask_b32_e64 v201, v207, v195, s[84:85]
	v_cndmask_b32_e64 v202, v154, v204, s[84:85]
	v_cndmask_b32_e64 v203, v155, v205, s[84:85]
	v_cndmask_b32_e64 v208, v210, v198, s[84:85]
	v_cndmask_b32_e64 v209, v211, v199, s[84:85]
	flat_store_dwordx4 v[208:209], v[200:203] offset:3584
	s_and_saveexec_b64 s[36:37], vcc
	s_cbranch_execz .LBB0_969
	v_cmp_gt_u32_e64 s[10:11], 61, v168
	v_mov_b32_e32 v154, v42
	v_mov_b32_e32 v155, v42
	s_and_b64 s[4:5], s[6:7], s[10:11]
	v_mov_b64_e32 v[158:159], v[154:155]
	s_and_saveexec_b64 s[46:47], s[4:5]
	s_cbranch_execz .LBB0_962
	v_add_u32_e32 v43, s34, v52
	v_add_u32_e32 v72, 0xfffac200, v43
	v_mov_b32_e32 v73, v42
	v_lshl_add_u64 v[72:73], v[44:45], 0, v[72:73]
	flat_load_dwordx2 v[158:159], v[72:73]

.LBB0_968:
	s_or_b64 exec, exec, s[10:11]
	v_add_co_u32_e32 v90, vcc, s62, v128
	v_pk_mul_f32 v[98:99], v[2:3], v[64:65]
	s_nop 0
	v_addc_co_u32_e32 v91, vcc, 0, v129, vcc
	flat_load_dwordx2 v[92:93], v[90:91] offset:1024
	v_lshl_add_u64 v[178:179], v[116:117], 0, s[90:91]
	v_lshl_add_u64 v[180:181], v[110:111], 0, s[90:91]
	v_lshl_add_u64 v[182:183], v[100:101], 0, s[90:91]
	global_load_dwordx2 v[184:185], v[178:179], off offset:-3072
	global_load_dwordx2 v[186:187], v[180:181], off offset:-3072
	global_load_dwordx2 v[188:189], v[182:183], off offset:-3072
	v_pk_mul_f32 v[102:103], v[0:1], v[62:63]
	v_lshlrev_b32_e32 v72, 16, v148
	v_and_b32_e32 v73, 0xffff0000, v148
	v_lshlrev_b32_e32 v76, 16, v149
	v_and_b32_e32 v77, 0xffff0000, v149
	v_pk_mul_f32 v[112:113], v[14:15], v[68:69]
	v_pk_mul_f32 v[114:115], v[12:13], v[66:67]
	v_pk_fma_f32 v[98:99], v[6:7], v[144:145], v[98:99]
	v_pk_fma_f32 v[102:103], v[4:5], v[142:143], v[102:103]
	v_lshlrev_b32_e32 v78, 16, v152
	v_and_b32_e32 v79, 0xffff0000, v152
	v_lshlrev_b32_e32 v80, 16, v153
	v_and_b32_e32 v81, 0xffff0000, v153
	v_pk_mul_f32 v[148:149], v[26:27], v[74:75]
	v_pk_mul_f32 v[152:153], v[24:25], v[70:71]
	v_pk_fma_f32 v[112:113], v[18:19], v[136:137], v[112:113]
	v_pk_fma_f32 v[114:115], v[16:17], v[134:135], v[114:115]
	v_pk_fma_f32 v[98:99], v[10:11], v[76:77], v[98:99]
	v_pk_fma_f32 v[102:103], v[8:9], v[72:73], v[102:103]
	v_lshlrev_b32_e32 v82, 16, v150
	v_and_b32_e32 v83, 0xffff0000, v150
	v_lshlrev_b32_e32 v84, 16, v151
	v_and_b32_e32 v85, 0xffff0000, v151
	v_pk_fma_f32 v[148:149], v[30:31], v[126:127], v[148:149]
	v_pk_fma_f32 v[152:153], v[28:29], v[122:123], v[152:153]
	v_pk_fma_f32 v[112:113], v[22:23], v[80:81], v[112:113]
	v_pk_fma_f32 v[114:115], v[20:21], v[78:79], v[114:115]
	v_pk_add_f32 v[98:99], v[38:39], v[98:99]
	v_pk_add_f32 v[102:103], v[36:37], v[102:103]
	v_pk_fma_f32 v[148:149], v[34:35], v[84:85], v[148:149]
	v_pk_fma_f32 v[152:153], v[32:33], v[82:83], v[152:153]
	v_pk_add_f32 v[98:99], v[98:99], v[112:113]
	v_pk_add_f32 v[102:103], v[102:103], v[114:115]
	v_pk_add_f32 v[98:99], v[98:99], v[148:149]
	v_pk_add_f32 v[102:103], v[102:103], v[152:153]
	v_mov_b64_e32 v[150:151], s[28:29]
	v_pk_mul_f32 v[112:113], v[98:99], v[98:99]
	v_pk_mul_f32 v[114:115], v[102:103], v[102:103]
	v_pk_fma_f32 v[112:113], v[112:113], s[26:27], v[150:151] op_sel_hi:[1,0,0] neg_lo:[1,0,0] neg_hi:[1,0,0]
	v_pk_fma_f32 v[114:115], v[114:115], s[26:27], v[150:151] op_sel_hi:[1,0,0] neg_lo:[1,0,0] neg_hi:[1,0,0]
	v_pk_mul_f32 v[112:113], v[98:99], v[112:113]
	v_pk_mul_f32 v[114:115], v[102:103], v[114:115]
	v_exp_f32_e32 v112, v112
	v_exp_f32_e32 v114, v114
	v_exp_f32_e32 v115, v115
	v_exp_f32_e32 v113, v113
	v_add_co_u32_e32 v148, vcc, s62, v116
	v_pk_add_f32 v[114:115], v[114:115], 1.0 op_sel_hi:[1,0]
	v_pk_add_f32 v[112:113], v[112:113], 1.0 op_sel_hi:[1,0]
	v_rcp_f32_e32 v114, v114
	v_rcp_f32_e32 v115, v115
	v_rcp_f32_e32 v112, v112
	v_rcp_f32_e32 v113, v113
	v_addc_co_u32_e32 v149, vcc, 0, v117, vcc
	v_pk_mul_f32 v[102:103], v[102:103], v[114:115]
	v_pk_mul_f32 v[98:99], v[98:99], v[112:113]
	v_pk_mul_f32 v[114:115], v[14:15], v[74:75]
	v_pk_mul_f32 v[152:153], v[26:27], v[88:89]
	v_pk_mul_f32 v[170:171], v[24:25], v[86:87]
	v_pk_fma_f32 v[114:115], v[18:19], v[126:127], v[114:115]
	v_pk_fma_f32 v[152:153], v[30:31], v[120:121], v[152:153]
	v_pk_fma_f32 v[170:171], v[28:29], v[118:119], v[170:171]
	v_pk_fma_f32 v[114:115], v[22:23], v[84:85], v[114:115]
	v_pk_mul_f32 v[172:173], v[24:25], v[94:95]
	v_pk_mul_f32 v[174:175], v[26:27], v[108:109]
	v_pk_fma_f32 v[172:173], v[28:29], v[130:131], v[172:173]
	v_pk_mul_f32 v[176:177], v[24:25], v[106:107]
	s_waitcnt vmcnt(0) lgkmcnt(0)
	v_lshlrev_b32_e32 v43, 16, v92
	v_and_b32_e32 v92, 0xffff0000, v92
	v_lshlrev_b32_e32 v112, 16, v93
	v_and_b32_e32 v93, 0xffff0000, v93
	v_mul_f32_e32 v92, v103, v92
	v_mul_f32_e32 v93, v99, v93
	v_mul_f32_e32 v43, v102, v43
	v_mul_f32_e32 v98, v98, v112
	v_cvt_pk_bf16_f32 v92, v43, v92
	v_cvt_pk_bf16_f32 v93, v98, v93
	v_mov_b64_e32 v[190:191], v[92:93]
	v_mov_b64_e32 v[192:193], v[90:91]
	v_mov_b64_e32 v[98:99], v[184:185]
	v_pk_mul_f32 v[102:103], v[2:3], v[68:69]
	v_pk_mul_f32 v[112:113], v[0:1], v[66:67]
	v_lshlrev_b32_e32 v90, 16, v146
	v_and_b32_e32 v91, 0xffff0000, v146
	v_lshlrev_b32_e32 v92, 16, v147
	v_and_b32_e32 v93, 0xffff0000, v147
	v_pk_mul_f32 v[146:147], v[12:13], v[70:71]
	v_pk_fma_f32 v[102:103], v[6:7], v[136:137], v[102:103]
	v_pk_fma_f32 v[112:113], v[4:5], v[134:135], v[112:113]
	v_pk_fma_f32 v[146:147], v[16:17], v[122:123], v[146:147]
	v_pk_fma_f32 v[102:103], v[10:11], v[80:81], v[102:103]
	v_pk_fma_f32 v[112:113], v[8:9], v[78:79], v[112:113]
	v_pk_fma_f32 v[146:147], v[20:21], v[82:83], v[146:147]
	v_pk_add_f32 v[102:103], v[38:39], v[102:103]
	v_pk_add_f32 v[112:113], v[36:37], v[112:113]
	v_pk_fma_f32 v[152:153], v[34:35], v[92:93], v[152:153]
	v_pk_fma_f32 v[170:171], v[32:33], v[90:91], v[170:171]
	v_pk_add_f32 v[102:103], v[102:103], v[114:115]
	v_pk_add_f32 v[112:113], v[112:113], v[146:147]
	v_pk_add_f32 v[102:103], v[102:103], v[152:153]
	v_pk_add_f32 v[112:113], v[112:113], v[170:171]
	v_pk_mul_f32 v[114:115], v[102:103], v[102:103]
	v_pk_mul_f32 v[146:147], v[112:113], v[112:113]
	v_pk_fma_f32 v[114:115], v[114:115], s[26:27], v[150:151] op_sel_hi:[1,0,0] neg_lo:[1,0,0] neg_hi:[1,0,0]
	v_pk_fma_f32 v[146:147], v[146:147], s[26:27], v[150:151] op_sel_hi:[1,0,0] neg_lo:[1,0,0] neg_hi:[1,0,0]
	v_pk_mul_f32 v[114:115], v[102:103], v[114:115]
	v_pk_mul_f32 v[146:147], v[112:113], v[146:147]
	v_exp_f32_e32 v114, v114
	v_exp_f32_e32 v146, v146
	v_exp_f32_e32 v147, v147
	v_exp_f32_e32 v115, v115
	v_add_co_u32_e32 v152, vcc, s62, v110
	v_pk_add_f32 v[146:147], v[146:147], 1.0 op_sel_hi:[1,0]
	v_pk_add_f32 v[114:115], v[114:115], 1.0 op_sel_hi:[1,0]
	v_rcp_f32_e32 v146, v146
	v_rcp_f32_e32 v147, v147
	v_rcp_f32_e32 v114, v114
	v_rcp_f32_e32 v115, v115
	v_addc_co_u32_e32 v153, vcc, 0, v111, vcc
	v_pk_mul_f32 v[112:113], v[112:113], v[146:147]
	v_pk_mul_f32 v[102:103], v[102:103], v[114:115]
	v_pk_mul_f32 v[146:147], v[14:15], v[88:89]
	v_pk_mul_f32 v[170:171], v[26:27], v[96:97]
	v_pk_fma_f32 v[146:147], v[18:19], v[120:121], v[146:147]
	v_pk_fma_f32 v[170:171], v[30:31], v[132:133], v[170:171]
	v_pk_fma_f32 v[146:147], v[22:23], v[92:93], v[146:147]
	s_nop 0
	v_lshlrev_b32_e32 v43, 16, v98
	v_and_b32_e32 v98, 0xffff0000, v98
	v_lshlrev_b32_e32 v114, 16, v99
	v_and_b32_e32 v99, 0xffff0000, v99
	v_mul_f32_e32 v98, v113, v98
	v_mul_f32_e32 v99, v103, v99
	v_mul_f32_e32 v43, v112, v43
	v_mul_f32_e32 v102, v102, v114
	v_cvt_pk_bf16_f32 v98, v43, v98
	v_cvt_pk_bf16_f32 v99, v102, v99
	s_nop 1
	v_mov_b32_dpp v204, v190 quad_perm:[1,0,3,2] row_mask:0xf bank_mask:0xf
	v_mov_b32_dpp v205, v191 quad_perm:[1,0,3,2] row_mask:0xf bank_mask:0xf
	v_mov_b32_dpp v206, v98 quad_perm:[1,0,3,2] row_mask:0xf bank_mask:0xf
	v_mov_b32_dpp v207, v99 quad_perm:[1,0,3,2] row_mask:0xf bank_mask:0xf
	v_lshl_add_u64 v[210:211], v[148:149], 0, s[86:87]
	v_cndmask_b32_e64 v200, v206, v190, s[84:85]
	v_cndmask_b32_e64 v201, v207, v191, s[84:85]
	v_cndmask_b32_e64 v202, v98, v204, s[84:85]
	v_cndmask_b32_e64 v203, v99, v205, s[84:85]
	v_cndmask_b32_e64 v208, v210, v192, s[84:85]
	v_cndmask_b32_e64 v209, v211, v193, s[84:85]
	flat_store_dwordx4 v[208:209], v[200:203] offset:1024
	v_mov_b64_e32 v[112:113], v[186:187]
	v_lshlrev_b32_e32 v98, 16, v124
	v_and_b32_e32 v99, 0xffff0000, v124
	v_lshlrev_b32_e32 v102, 16, v125
	v_and_b32_e32 v103, 0xffff0000, v125
	v_pk_mul_f32 v[114:115], v[2:3], v[74:75]
	v_pk_mul_f32 v[124:125], v[0:1], v[70:71]
	v_pk_mul_f32 v[148:149], v[12:13], v[86:87]
	v_pk_fma_f32 v[114:115], v[6:7], v[126:127], v[114:115]
	v_pk_fma_f32 v[124:125], v[4:5], v[122:123], v[124:125]
	v_pk_fma_f32 v[148:149], v[16:17], v[118:119], v[148:149]
	v_pk_fma_f32 v[114:115], v[10:11], v[84:85], v[114:115]
	v_pk_fma_f32 v[124:125], v[8:9], v[82:83], v[124:125]
	v_pk_fma_f32 v[148:149], v[20:21], v[90:91], v[148:149]
	v_pk_add_f32 v[114:115], v[38:39], v[114:115]
	v_pk_add_f32 v[124:125], v[36:37], v[124:125]
	v_pk_fma_f32 v[170:171], v[34:35], v[102:103], v[170:171]
	v_pk_fma_f32 v[172:173], v[32:33], v[98:99], v[172:173]
	v_pk_add_f32 v[114:115], v[114:115], v[146:147]
	v_pk_add_f32 v[124:125], v[124:125], v[148:149]
	v_pk_add_f32 v[114:115], v[114:115], v[170:171]
	v_pk_add_f32 v[124:125], v[124:125], v[172:173]
	v_pk_mul_f32 v[146:147], v[114:115], v[114:115]
	v_pk_mul_f32 v[148:149], v[124:125], v[124:125]
	v_pk_fma_f32 v[146:147], v[146:147], s[26:27], v[150:151] op_sel_hi:[1,0,0] neg_lo:[1,0,0] neg_hi:[1,0,0]
	v_pk_fma_f32 v[148:149], v[148:149], s[26:27], v[150:151] op_sel_hi:[1,0,0] neg_lo:[1,0,0] neg_hi:[1,0,0]
	v_pk_mul_f32 v[146:147], v[114:115], v[146:147]
	v_pk_mul_f32 v[148:149], v[124:125], v[148:149]
	v_exp_f32_e32 v146, v146
	v_exp_f32_e32 v148, v148
	v_exp_f32_e32 v149, v149
	v_exp_f32_e32 v147, v147
	v_add_co_u32_e32 v170, vcc, s62, v100
	v_pk_add_f32 v[148:149], v[148:149], 1.0 op_sel_hi:[1,0]
	v_pk_add_f32 v[146:147], v[146:147], 1.0 op_sel_hi:[1,0]
	v_rcp_f32_e32 v148, v148
	v_rcp_f32_e32 v149, v149
	v_rcp_f32_e32 v146, v146
	v_rcp_f32_e32 v147, v147
	v_addc_co_u32_e32 v171, vcc, 0, v101, vcc
	v_pk_mul_f32 v[124:125], v[124:125], v[148:149]
	v_pk_mul_f32 v[114:115], v[114:115], v[146:147]
	v_mov_b64_e32 v[148:149], v[158:159]
	v_pk_fma_f32 v[158:159], v[30:31], v[140:141], v[174:175]
	v_pk_fma_f32 v[174:175], v[28:29], v[138:139], v[176:177]
	s_nop 0
	v_lshlrev_b32_e32 v43, 16, v112
	v_and_b32_e32 v112, 0xffff0000, v112
	v_lshlrev_b32_e32 v146, 16, v113
	v_and_b32_e32 v113, 0xffff0000, v113
	v_mul_f32_e32 v112, v125, v112
	v_mul_f32_e32 v113, v115, v113
	v_mul_f32_e32 v43, v124, v43
	v_mul_f32_e32 v114, v114, v146
	v_cvt_pk_bf16_f32 v112, v43, v112
	v_cvt_pk_bf16_f32 v113, v114, v113
	v_mov_b64_e32 v[194:195], v[112:113]
	v_mov_b64_e32 v[198:199], v[152:153]
	v_mov_b64_e32 v[172:173], v[188:189]
	v_lshlrev_b32_e32 v112, 16, v104
	v_and_b32_e32 v113, 0xffff0000, v104
	v_lshlrev_b32_e32 v114, 16, v105
	v_and_b32_e32 v115, 0xffff0000, v105
	v_pk_mul_f32 v[104:105], v[2:3], v[88:89]
	v_pk_mul_f32 v[124:125], v[0:1], v[86:87]
	v_pk_mul_f32 v[146:147], v[14:15], v[96:97]
	v_pk_mul_f32 v[152:153], v[12:13], v[94:95]
	v_pk_fma_f32 v[104:105], v[6:7], v[120:121], v[104:105]
	v_pk_fma_f32 v[124:125], v[4:5], v[118:119], v[124:125]
	v_pk_fma_f32 v[146:147], v[18:19], v[132:133], v[146:147]
	v_pk_fma_f32 v[152:153], v[16:17], v[130:131], v[152:153]
	v_pk_fma_f32 v[104:105], v[10:11], v[92:93], v[104:105]
	v_pk_fma_f32 v[124:125], v[8:9], v[90:91], v[124:125]
	v_pk_fma_f32 v[146:147], v[22:23], v[102:103], v[146:147]
	v_pk_fma_f32 v[152:153], v[20:21], v[98:99], v[152:153]
	v_pk_add_f32 v[104:105], v[38:39], v[104:105]
	v_pk_add_f32 v[124:125], v[36:37], v[124:125]
	v_pk_fma_f32 v[158:159], v[34:35], v[114:115], v[158:159]
	v_pk_fma_f32 v[174:175], v[32:33], v[112:113], v[174:175]
	v_pk_add_f32 v[104:105], v[104:105], v[146:147]
	v_pk_add_f32 v[124:125], v[124:125], v[152:153]
	v_pk_add_f32 v[104:105], v[104:105], v[158:159]
	v_pk_add_f32 v[158:159], v[124:125], v[174:175]
	v_pk_mul_f32 v[124:125], v[104:105], v[104:105]
	v_pk_mul_f32 v[146:147], v[158:159], v[158:159]
	v_pk_fma_f32 v[124:125], v[124:125], s[26:27], v[150:151] op_sel_hi:[1,0,0] neg_lo:[1,0,0] neg_hi:[1,0,0]
	v_pk_fma_f32 v[146:147], v[146:147], s[26:27], v[150:151] op_sel_hi:[1,0,0] neg_lo:[1,0,0] neg_hi:[1,0,0]
	v_pk_mul_f32 v[124:125], v[104:105], v[124:125]
	v_pk_mul_f32 v[146:147], v[158:159], v[146:147]
	v_exp_f32_e32 v124, v124
	v_exp_f32_e32 v146, v146
	v_exp_f32_e32 v147, v147
	v_exp_f32_e32 v125, v125
	v_mov_b64_e32 v[152:153], v[154:155]
	v_mov_b64_e32 v[150:151], v[156:157]
	v_pk_add_f32 v[146:147], v[146:147], 1.0 op_sel_hi:[1,0]
	v_pk_add_f32 v[124:125], v[124:125], 1.0 op_sel_hi:[1,0]
	v_rcp_f32_e32 v154, v146
	v_rcp_f32_e32 v155, v147
	v_rcp_f32_e32 v156, v124
	v_rcp_f32_e32 v157, v125
	v_mov_b64_e32 v[146:147], v[160:161]
	v_pk_mul_f32 v[154:155], v[158:159], v[154:155]
	v_mov_b64_e32 v[124:125], v[162:163]
	v_pk_mul_f32 v[104:105], v[104:105], v[156:157]
	s_nop 0
	v_and_b32_e32 v158, 0xffff0000, v173
	v_lshlrev_b32_e32 v43, 16, v172
	v_and_b32_e32 v156, 0xffff0000, v172
	v_lshlrev_b32_e32 v157, 16, v173
	v_mul_f32_e32 v105, v105, v158
	v_mul_f32_e32 v43, v154, v43
	v_mul_f32_e32 v154, v155, v156
	v_mul_f32_e32 v155, v104, v157
	v_cvt_pk_bf16_f32 v104, v43, v154
	v_cvt_pk_bf16_f32 v105, v155, v105
	s_nop 1
	v_mov_b32_dpp v204, v194 quad_perm:[1,0,3,2] row_mask:0xf bank_mask:0xf
	v_mov_b32_dpp v205, v195 quad_perm:[1,0,3,2] row_mask:0xf bank_mask:0xf
	v_mov_b32_dpp v206, v104 quad_perm:[1,0,3,2] row_mask:0xf bank_mask:0xf
	v_mov_b32_dpp v207, v105 quad_perm:[1,0,3,2] row_mask:0xf bank_mask:0xf
	v_lshl_add_u64 v[210:211], v[170:171], 0, s[86:87]
	v_cndmask_b32_e64 v200, v206, v194, s[84:85]
	v_cndmask_b32_e64 v201, v207, v195, s[84:85]
	v_cndmask_b32_e64 v202, v104, v204, s[84:85]
	v_cndmask_b32_e64 v203, v105, v205, s[84:85]
	v_cndmask_b32_e64 v208, v210, v198, s[84:85]
	v_cndmask_b32_e64 v209, v211, v199, s[84:85]
	flat_store_dwordx4 v[208:209], v[200:203] offset:1024
	v_mov_b64_e32 v[104:105], v[164:165]
